# v7 + grid barriers after in-proj GEMM and after SGU replaced by 32-WG same-XCD group barriers (layer-0 chain is row-local per XCD group)
# speedup vs baseline: 1.0294x; 1.0095x over previous
; #define LAS __attribute__((address_space(3)))
; __device__ __forceinline__ unsigned xb_add(unsigned* p, unsigned v) { return __hip_atomic_fetch_add(p, v, __ATOMIC_RELAXED, __HIP_MEMORY_SCOPE_AGENT); }
; __device__ __forceinline__ unsigned xb_xcc_id() { return (unsigned)__builtin_amdgcn_s_getreg((3 << 11) | 20) & 0xFu; }
; __device__ __forceinline__ XcdBarrier xcd_barrier_post(unsigned* bar, volatile LAS unsigned* st) {
;     XcdBarrier b; b.bar = bar; b.x = xb_xcc_id(); b.st = st;
;     if (threadIdx.x == 0) (void)xb_add(&bar[XB_XCNT(b.x)], 1u);
;     return b;
; }
; __global__ void __launch_bounds__(NTHREADS, 2) mk_fwd(Params P) {
;     ...
;     volatile LAS unsigned* xst = (volatile LAS unsigned*)(lds + LDS_MAIN);
;     if (threadIdx.x == 0) { xst[0] = 0u; xst[1] = 0u; }
;     __syncthreads();
;     XcdBarrier xbar; xbar.bar = (unsigned*)(ws + WS_BAR); xbar.x = 0; xbar.st = xst;
;     if (hi - lo > 1) xbar = xcd_barrier_post((unsigned*)(ws + WS_BAR), xst);
.LBB0_2:
	s_or_b64 exec, exec, s[4:5]
	s_waitcnt lgkmcnt(0)
	s_add_u32 s54, s40, 0x3d00000
	s_addc_u32 s55, s41, 0
	s_sub_i32 s3, s43, s42
	s_cmp_lt_i32 s3, 2
	s_barrier
	s_cbranch_scc1 .LBB0_7
	s_getreg_b32 s3, hwreg(HW_REG_XCC_ID, 0, 4)
	s_and_b32 s33, s3, 15
	s_and_saveexec_b64 s[4:5], s[12:13]
	s_cbranch_execz .LBB0_6
	s_mov_b64 s[8:9], exec
	v_mbcnt_lo_u32_b32 v1, s8, 0
	v_mbcnt_hi_u32_b32 v1, s9, v1
	v_cmp_eq_u32_e32 vcc, 0, v1
	s_and_b64 s[10:11], exec, vcc
	s_mov_b64 exec, s[10:11]
	s_cbranch_execz .LBB0_6
	s_lshl_b32 s3, s33, 8
	s_bcnt1_i32_b64 s8, s[8:9]
	v_mov_b32_e32 v1, s3
	v_mov_b32_e32 v2, s8
	global_atomic_add v1, v2, s[54:55] offset:1024
	s_and_b32 s3, s2, 7
	s_lshl_b32 s3, s3, 6
	s_add_i32 s3, s3, 0x8008
	v_mov_b32_e32 v1, s3
	s_lshl_b32 s8, 1, s33
	v_mov_b32_e32 v2, s8
	global_atomic_or v1, v2, s[54:55]

;     __device__ bool next(int i, Unit& u) const {
;         const long L = (long)i * G + c; if (L >= nwg) return false;
;         int wgid = (int)L; { const int q = nwg / NXCD, r = nwg % NXCD, xcd = wgid % NXCD, off = wgid / NXCD; wgid = (xcd < r ? xcd * (q + 1) : r * (q + 1) + (xcd - r) * q) + off; }
;         const int nig = WGM * nN, gid = wgid / nig, fm = gid * WGM, gsz = (nM - fm) < WGM ? (nM - fm) : WGM;
;         u.pm = fm + ((wgid % nig) % gsz); u.pn = (wgid % nig) / gsz; return true;
; __global__ void __launch_bounds__(NTHREADS, 2) mk_fwd(Params P) {
;     ...
;         pg8::Gemm g{SLOTA, WINA, MTOK, 6144, 2048, 1 << 30, 0}; pg8::StaticOrder S; S.init(MTOK, 6144, G, bid);
.LBB0_143:
	s_and_b32 s98, s2, 7
	s_lshl_b32 s98, s98, 6
	s_add_i32 s98, s98, 0x8008
	v_mov_b32_e32 v255, s98
	global_load_dword v255, v255, s[54:55] sc1
	s_waitcnt lgkmcnt(0)
	s_add_u32 s16, s40, 0x3a00000
	s_addc_u32 s17, s41, 0
	s_add_u32 s20, s40, 0x4000000
	s_addc_u32 s21, s41, 0
	s_add_u32 s8, s40, 0x8800000
	s_addc_u32 s9, s41, 0
	s_add_u32 s10, s40, 0xa800000
	s_addc_u32 s11, s41, 0
	s_cmp_lt_i32 s42, 2
	s_cselect_b64 s[4:5], -1, 0
	s_and_b64 s[0:1], s[4:5], s[0:1]
	s_andn2_b64 vcc, exec, s[0:1]
	s_cbranch_vccnz .LBB0_182
	s_cmpk_lt_i32 s2, 0x300
	s_cselect_b64 s[4:5], -1, 0
	s_cmpk_gt_i32 s2, 0x2ff
	v_readfirstlane_b32 s6, v164
	s_cbranch_scc1 .LBB0_146
	s_ashr_i32 s3, s2, 31
	s_lshr_b32 s3, s3, 29
	s_add_i32 s3, s2, s3
	s_ashr_i32 s7, s3, 3
	s_and_b32 s3, s3, -8
	s_sub_i32 s3, s2, s3
	s_cmp_lt_i32 s3, 0
	s_movk_i32 s18, 0x61
	s_cselect_b32 s18, s18, 0x60
	s_mul_i32 s3, s3, s18
	s_add_i32 s3, s3, s7
	s_mul_hi_i32 s7, s3, 0x2aaaaaab
	s_lshr_b32 s18, s7, 31
	s_ashr_i32 s7, s7, 4
	s_add_i32 s7, s7, s18
	s_lshl_b32 s18, s7, 2
	s_mulk_i32 s7, 0x60
	s_sub_i32 s3, s3, s7
	s_bfe_i32 s7, s3, 0x80000
	s_bfe_u32 s7, s7, 0x2000d
	s_add_i32 s7, s3, s7
	s_bfe_i32 s19, s7, 0x80000
	s_and_b32 s7, s7, 0xfc
	s_sub_i32 s3, s3, s7
	s_sext_i32_i16 s19, s19
	s_sext_i32_i8 s3, s3
	s_add_i32 s18, s18, s3
	s_ashr_i32 s70, s19, 2

; __device__ __forceinline__ unsigned xb_ld(unsigned* p)              { return __hip_atomic_load(p, __ATOMIC_RELAXED, __HIP_MEMORY_SCOPE_AGENT); }
; __device__ __forceinline__ unsigned xb_add(unsigned* p, unsigned v) { return __hip_atomic_fetch_add(p, v, __ATOMIC_RELAXED, __HIP_MEMORY_SCOPE_AGENT); }
; #define XB_SPIN(cond, bar) do { unsigned _sp = 0; while (cond) { __builtin_amdgcn_s_sleep(1); \
;     if ((++_sp & 255u) == 0u) { if (xb_ld(&(bar)[XB_TMO])) break; if (_sp > XB_SPIN_CAP) { atomicAdd(&(bar)[XB_TMO], 1u); break; } } } } while (0)
; __device__ __forceinline__ void xcd_barrier(const XcdBarrier& b) {
;     asm volatile("s_waitcnt vmcnt(0)" ::: "memory");
;     __syncthreads();
;     if (threadIdx.x == 0) {
;         unsigned* bar = b.bar;
;         __builtin_amdgcn_s_waitcnt(0);
;         unsigned nloc = b.st[0], nx = b.st[1];
;         if (nloc == 0u) { xcd_barrier_complete(bar, b.x, nloc, nx); b.st[0] = nloc; b.st[1] = nx; }
;         const unsigned old = xb_add(&bar[XB_XSUB(b.x)], 1u);
;         const unsigned gen = old / nloc;
;         if (old + 1u == (gen + 1u) * nloc) {
;             __builtin_amdgcn_fence(__ATOMIC_RELEASE, "agent");
;             asm volatile("s_waitcnt vmcnt(0)" ::: "memory");
;             const unsigned og = xb_add(&bar[XB_TOP], 1u);
;             const unsigned tg = og / nx;
;             if (og + 1u == (tg + 1u) * nx) xb_add(&bar[XB_TOPGEN], 1u);
;             else XB_SPIN(xb_ld(&bar[XB_TOPGEN]) == tg, bar);
;             __builtin_amdgcn_fence(__ATOMIC_ACQUIRE, "agent");
;             xb_add(&bar[XB_XGEN(b.x)], 1u);
;             asm volatile("s_waitcnt vmcnt(0)" ::: "memory");
;         } else {
;             XB_SPIN(xb_ld(&bar[XB_XGEN(b.x)]) == gen, bar);
;             __builtin_amdgcn_fence(__ATOMIC_ACQUIRE, "agent");
;             asm volatile("s_waitcnt vmcnt(0)" ::: "memory");
;         }
;     }
;     __syncthreads();
; }
.LBB0_182:
	s_cmp_gt_i32 s43, 2
	s_cselect_b64 s[4:5], -1, 0
	s_and_b64 s[0:1], s[0:1], s[4:5]
	s_andn2_b64 vcc, exec, s[0:1]
	s_cbranch_vccnz .LBB0_232
	s_waitcnt vmcnt(0)
	s_waitcnt vmcnt(0) lgkmcnt(0)
	s_barrier
	s_and_saveexec_b64 s[0:1], s[12:13]
	s_cbranch_execz .LBB0_231
	s_and_b32 s98, s2, 7
	s_lshl_b32 s98, s98, 6
	s_add_i32 s98, s98, 0x8000
	v_mov_b32_e32 v250, s98
	v_mov_b32_e32 v252, 1
	v_readfirstlane_b32 s99, v255
	s_bcnt1_i32_b32 s99, s99
	v_mov_b32_e32 v253, 0x2000c
	v_mov_b32_e32 v254, s99
	ds_write_b32 v253, v254
	s_cmp_eq_u32 s99, 1
	s_cbranch_scc1 .Lgb1_fast
	buffer_wbl2 sc1
	s_waitcnt vmcnt(0)
.Lgb1_fast:
	global_atomic_add v250, v252, s[54:55]
	s_mov_b32 s99, 0
.Lgb1_spin:
	global_load_dword v251, v250, s[54:55] sc1
	s_waitcnt vmcnt(0)
	v_readfirstlane_b32 s98, v251
	s_cmp_ge_u32 s98, 32
	s_cbranch_scc1 .Lgb1_ok
	s_sleep 1
	s_add_u32 s99, s99, 1
	s_cmp_lt_u32 s99, 0x40000
	s_cbranch_scc1 .Lgb1_spin

; __device__ __forceinline__ unsigned xb_ld(unsigned* p)              { return __hip_atomic_load(p, __ATOMIC_RELAXED, __HIP_MEMORY_SCOPE_AGENT); }
; __device__ __forceinline__ unsigned xb_add(unsigned* p, unsigned v) { return __hip_atomic_fetch_add(p, v, __ATOMIC_RELAXED, __HIP_MEMORY_SCOPE_AGENT); }
; #define XB_SPIN(cond, bar) do { unsigned _sp = 0; while (cond) { __builtin_amdgcn_s_sleep(1); \
;     if ((++_sp & 255u) == 0u) { if (xb_ld(&(bar)[XB_TMO])) break; if (_sp > XB_SPIN_CAP) { atomicAdd(&(bar)[XB_TMO], 1u); break; } } } } while (0)
; __device__ __forceinline__ void xcd_barrier(const XcdBarrier& b) {
;     asm volatile("s_waitcnt vmcnt(0)" ::: "memory");
;     __syncthreads();
;     if (threadIdx.x == 0) {
;         unsigned* bar = b.bar;
;         __builtin_amdgcn_s_waitcnt(0);
;         unsigned nloc = b.st[0], nx = b.st[1];
;         if (nloc == 0u) { xcd_barrier_complete(bar, b.x, nloc, nx); b.st[0] = nloc; b.st[1] = nx; }
;         const unsigned old = xb_add(&bar[XB_XSUB(b.x)], 1u);
;         const unsigned gen = old / nloc;
;         if (old + 1u == (gen + 1u) * nloc) {
;             __builtin_amdgcn_fence(__ATOMIC_RELEASE, "agent");
;             asm volatile("s_waitcnt vmcnt(0)" ::: "memory");
;             const unsigned og = xb_add(&bar[XB_TOP], 1u);
;             const unsigned tg = og / nx;
;             if (og + 1u == (tg + 1u) * nx) xb_add(&bar[XB_TOPGEN], 1u);
;             else XB_SPIN(xb_ld(&bar[XB_TOPGEN]) == tg, bar);
;             __builtin_amdgcn_fence(__ATOMIC_ACQUIRE, "agent");
;             xb_add(&bar[XB_XGEN(b.x)], 1u);
;             asm volatile("s_waitcnt vmcnt(0)" ::: "memory");
;         } else {
;             XB_SPIN(xb_ld(&bar[XB_XGEN(b.x)]) == gen, bar);
;             __builtin_amdgcn_fence(__ATOMIC_ACQUIRE, "agent");
;             asm volatile("s_waitcnt vmcnt(0)" ::: "memory");
;         }
;     }
;     __syncthreads();
; }
.LBB0_241:
	s_cmp_gt_i32 s43, 3
	s_cselect_b64 s[0:1], -1, 0
	s_and_b64 s[4:5], s[4:5], s[0:1]
	s_andn2_b64 vcc, exec, s[4:5]
	s_cbranch_vccnz .LBB0_291
	s_waitcnt vmcnt(0)
	s_waitcnt vmcnt(0) lgkmcnt(0)
	s_barrier
	s_and_saveexec_b64 s[4:5], s[12:13]
	s_cbranch_execz .LBB0_290
	s_and_b32 s98, s2, 7
	s_lshl_b32 s98, s98, 6
	s_add_i32 s98, s98, 0x8000
	v_mov_b32_e32 v250, s98
	v_mov_b32_e32 v252, 1
	v_mov_b32_e32 v253, 0x2000c
	ds_read_b32 v254, v253
	s_waitcnt lgkmcnt(0)
	v_readfirstlane_b32 s99, v254
	s_cmp_eq_u32 s99, 1
	s_cbranch_scc1 .Lgb2_fast
	buffer_wbl2 sc1
	s_waitcnt vmcnt(0)
.Lgb2_fast:
	global_atomic_add v250, v252, s[54:55] offset:4
	s_mov_b32 s99, 0
.Lgb2_spin:
	global_load_dword v251, v250, s[54:55] offset:4 sc1
	s_waitcnt vmcnt(0)
	v_readfirstlane_b32 s98, v251
	s_cmp_ge_u32 s98, 32
	s_cbranch_scc1 .Lgb2_ok
	s_sleep 1
	s_add_u32 s99, s99, 1
	s_cmp_lt_u32 s99, 0x40000
	s_cbranch_scc1 .Lgb2_spin
.Lgb2_ok:
	buffer_inv sc1
	s_waitcnt vmcnt(0)
.LBB0_290:
	s_or_b64 exec, exec, s[4:5]
	s_waitcnt lgkmcnt(0)
	s_barrier

; __device__ __forceinline__ unsigned xb_ld(unsigned* p)              { return __hip_atomic_load(p, __ATOMIC_RELAXED, __HIP_MEMORY_SCOPE_AGENT); }
; __device__ __forceinline__ unsigned xb_add(unsigned* p, unsigned v) { return __hip_atomic_fetch_add(p, v, __ATOMIC_RELAXED, __HIP_MEMORY_SCOPE_AGENT); }
; #define XB_SPIN(cond, bar) do { unsigned _sp = 0; while (cond) { __builtin_amdgcn_s_sleep(1); \
;     if ((++_sp & 255u) == 0u) { if (xb_ld(&(bar)[XB_TMO])) break; if (_sp > XB_SPIN_CAP) { atomicAdd(&(bar)[XB_TMO], 1u); break; } } } } while (0)
; __device__ __forceinline__ void xcd_barrier(const XcdBarrier& b) {
;     asm volatile("s_waitcnt vmcnt(0)" ::: "memory");
;     __syncthreads();
;     if (threadIdx.x == 0) {
;         unsigned* bar = b.bar;
;         __builtin_amdgcn_s_waitcnt(0);
;         unsigned nloc = b.st[0], nx = b.st[1];
;         if (nloc == 0u) { xcd_barrier_complete(bar, b.x, nloc, nx); b.st[0] = nloc; b.st[1] = nx; }
;         const unsigned old = xb_add(&bar[XB_XSUB(b.x)], 1u);
;         const unsigned gen = old / nloc;
;         if (old + 1u == (gen + 1u) * nloc) {
;             __builtin_amdgcn_fence(__ATOMIC_RELEASE, "agent");
;             asm volatile("s_waitcnt vmcnt(0)" ::: "memory");
;             const unsigned og = xb_add(&bar[XB_TOP], 1u);
;             const unsigned tg = og / nx;
;             if (og + 1u == (tg + 1u) * nx) xb_add(&bar[XB_TOPGEN], 1u);
;             else XB_SPIN(xb_ld(&bar[XB_TOPGEN]) == tg, bar);
;             __builtin_amdgcn_fence(__ATOMIC_ACQUIRE, "agent");
;             xb_add(&bar[XB_XGEN(b.x)], 1u);
;             asm volatile("s_waitcnt vmcnt(0)" ::: "memory");
;         } else {
;             XB_SPIN(xb_ld(&bar[XB_XGEN(b.x)]) == gen, bar);
;             __builtin_amdgcn_fence(__ATOMIC_ACQUIRE, "agent");
;             asm volatile("s_waitcnt vmcnt(0)" ::: "memory");
;         }
;     }
;     __syncthreads();
; }
.LBB0_366:
	s_cmp_gt_u32 s43, 4
	s_cselect_b64 s[0:1], -1, 0
	s_and_b64 s[0:1], s[16:17], s[0:1]
	s_andn2_b64 vcc, exec, s[0:1]
	s_cbranch_vccnz .LBB0_416
	s_waitcnt vmcnt(0)
	s_waitcnt vmcnt(0) lgkmcnt(0)
	s_barrier
	s_and_saveexec_b64 s[0:1], s[12:13]
	s_cbranch_execz .LBB0_415
	s_and_b32 s98, s2, 7
	s_lshl_b32 s98, s98, 2
	s_bfe_u32 s99, s2, 0x20003
	s_or_b32 s98, s98, s99
	s_lshl_b32 s98, s98, 6
	s_add_i32 s98, s98, 0xa400
	v_mov_b32_e32 v250, s98
	v_mov_b32_e32 v252, 1
	v_mov_b32_e32 v253, 0x2000c
	ds_read_b32 v254, v253
	s_waitcnt lgkmcnt(0)
	v_readfirstlane_b32 s99, v254
	s_cmp_eq_u32 s99, 1
	s_cbranch_scc1 .Lpb3_fast
	buffer_wbl2 sc1
	s_waitcnt vmcnt(0)
